# v38 + one static s_setprio 1 for the younger half (waves 4-7) at each attention unit start; the older-half variant was neutral earlier
# baseline (speedup 1.0000x reference)
.LBB0_950:
	v_readfirstlane_b32 s22, v0
	s_cmpk_ge_u32 s22, 0x100
	s_cbranch_scc0 .Lprio_skip_b_lat
	s_setprio 1

.LBB0_961:
	v_readfirstlane_b32 s4, v0
	s_cmpk_ge_u32 s4, 0x100
	s_cbranch_scc0 .Lprio_skip_b_ctx
	s_setprio 1

.LBB0_1012:
	v_readfirstlane_b32 s16, v0
	s_cmpk_ge_u32 s16, 0x100
	s_cbranch_scc0 .Lprio_skip_a_lat
	s_setprio 1
